# v16 + attention sample units: stage_sample's six serialized load->convert round trips replaced by all loads first, one wait, then conversions and LDS writes
# speedup vs baseline: 1.0068x; 1.0023x over previous
.LBB0_1224:
	s_add_i32 s0, s59, 0xfffffe00
	s_lshr_b32 s74, s0, 1
	s_lshl_b32 s61, s74, 2
	s_addk_i32 s61, 0x3f80
	s_and_b32 s60, s66, 64
	s_lshl_b32 vcc_lo, s74, 7
	v_or_b32_e32 v8, s60, v124
	v_readlane_b32 s56, v253, 24
	v_readlane_b32 s57, v253, 25
	v_readlane_b32 s78, v253, 26
	v_readlane_b32 s79, v253, 27
	s_mov_b64 s[0:1], exec
	v_readlane_b32 s74, v253, 36
	v_readlane_b32 s75, v253, 37
	s_nop 0
	s_and_b64 s[74:75], s[0:1], s[74:75]
	s_mov_b64 exec, s[74:75]
	s_cbranch_execz .Latt_st_c0
	v_mov_b32_e32 v0, 0
	v_mov_b32_e32 v1, 0
	v_mov_b32_e32 v2, 0
	v_mov_b32_e32 v3, 0
	v_mov_b32_e32 v4, 0
	v_mov_b32_e32 v5, 0
	v_mov_b32_e32 v6, 0
	v_mov_b32_e32 v7, 0
	v_readlane_b32 s54, v253, 38
	v_readlane_b32 vcc_hi, v253, 39
	s_nop 0
	s_and_b32 exec_lo, exec_lo, s54
	s_and_b32 exec_hi, exec_hi, vcc_hi
	s_cbranch_execz .Latt_st_c0
	v_add_u32_e32 v18, s61, v125
	s_movk_i32 s54, 0x1600
	v_mul_lo_u32 v18, v18, s54
	v_mov_b32_e32 v19, v16
	v_lshl_add_u64 v[18:19], s[52:53], 0, v[18:19]
	s_lshl_b32 s54, s60, 1
	v_lshl_add_u64 v[18:19], v[18:19], 0, s[54:55]
	v_lshlrev_b32_e32 v20, 1, v124
	v_mov_b32_e32 v21, v16
	v_lshl_add_u64 v[18:19], v[18:19], 0, v[20:21]
	global_load_dwordx4 v[0:3], v[18:19], off offset:1024
	global_load_dwordx4 v[4:7], v[18:19], off offset:1280
.Latt_st_c0:
	s_andn2_b64 exec, s[0:1], s[74:75]
	s_cbranch_execz .Latt_st_n0
	v_add_u32_e32 v18, vcc_lo, v125
	v_ashrrev_i32_e32 v19, 31, v18
	v_lshlrev_b64 v[22:23], 9, v[18:19]
	v_lshl_or_b32 v22, v8, 2, v22
	v_lshl_add_u64 v[18:19], s[56:57], 0, v[22:23]
	v_lshl_add_u64 v[20:21], s[78:79], 0, v[22:23]
	global_load_dwordx4 v[42:45], v[18:19], off
	global_load_dwordx4 v[46:49], v[18:19], off offset:16
	global_load_dwordx4 v[50:53], v[20:21], off
	global_load_dwordx4 v[54:57], v[20:21], off offset:16
.Latt_st_n0:
	v_readlane_b32 s74, v253, 40
	v_readlane_b32 s75, v253, 41
	s_nop 0
	s_and_b64 s[74:75], s[0:1], s[74:75]
	s_mov_b64 exec, s[74:75]
	s_cbranch_execz .Latt_st_c1
	v_mov_b32_e32 v58, 0
	v_mov_b32_e32 v59, 0
	v_mov_b32_e32 v60, 0
	v_mov_b32_e32 v61, 0
	v_mov_b32_e32 v62, 0
	v_mov_b32_e32 v63, 0
	v_mov_b32_e32 v64, 0
	v_mov_b32_e32 v65, 0
	v_readlane_b32 s54, v253, 42
	v_readlane_b32 vcc_hi, v253, 43
	s_nop 0
	s_and_b32 exec_lo, exec_lo, s54
	s_and_b32 exec_hi, exec_hi, vcc_hi
	s_cbranch_execz .Latt_st_c1
	v_add_u32_e32 v18, s61, v144
	s_movk_i32 s54, 0x1600
	v_mul_lo_u32 v18, v18, s54
	v_mov_b32_e32 v19, v16
	v_lshl_add_u64 v[18:19], s[52:53], 0, v[18:19]
	s_lshl_b32 s54, s60, 1
	v_lshl_add_u64 v[18:19], v[18:19], 0, s[54:55]
	v_lshlrev_b32_e32 v20, 1, v124
	v_mov_b32_e32 v21, v16
	v_lshl_add_u64 v[18:19], v[18:19], 0, v[20:21]
	global_load_dwordx4 v[58:61], v[18:19], off offset:1024
	global_load_dwordx4 v[62:65], v[18:19], off offset:1280
.Latt_st_c1:
	s_andn2_b64 exec, s[0:1], s[74:75]
	s_cbranch_execz .Latt_st_n1
	v_add_u32_e32 v18, vcc_lo, v144
	v_ashrrev_i32_e32 v19, 31, v18
	v_lshlrev_b64 v[22:23], 9, v[18:19]
	v_lshl_or_b32 v22, v8, 2, v22
	v_lshl_add_u64 v[18:19], s[56:57], 0, v[22:23]
	v_lshl_add_u64 v[20:21], s[78:79], 0, v[22:23]
	global_load_dwordx4 v[66:69], v[18:19], off
	global_load_dwordx4 v[70:73], v[18:19], off offset:16
	global_load_dwordx4 v[74:77], v[20:21], off
	global_load_dwordx4 v[78:81], v[20:21], off offset:16
.Latt_st_n1:
	s_and_b64 s[74:75], s[0:1], s[82:83]
	s_mov_b64 exec, s[74:75]
	s_cbranch_execz .Latt_st_c2
	v_mov_b32_e32 v82, 0
	v_mov_b32_e32 v83, 0
	v_mov_b32_e32 v84, 0
	v_mov_b32_e32 v85, 0
	v_mov_b32_e32 v86, 0
	v_mov_b32_e32 v87, 0
	v_mov_b32_e32 v88, 0
	v_mov_b32_e32 v89, 0
	v_readlane_b32 s54, v253, 44
	v_readlane_b32 vcc_hi, v253, 45
	s_nop 0
	s_and_b32 exec_lo, exec_lo, s54
	s_and_b32 exec_hi, exec_hi, vcc_hi
	s_cbranch_execz .Latt_st_c2
	v_add_u32_e32 v18, s61, v147
	s_movk_i32 s54, 0x1600
	v_mul_lo_u32 v18, v18, s54
	v_mov_b32_e32 v19, v16
	v_lshl_add_u64 v[18:19], s[52:53], 0, v[18:19]
	s_lshl_b32 s54, s60, 1
	v_lshl_add_u64 v[18:19], v[18:19], 0, s[54:55]
	v_lshlrev_b32_e32 v20, 1, v124
	v_mov_b32_e32 v21, v16
	v_lshl_add_u64 v[18:19], v[18:19], 0, v[20:21]
	global_load_dwordx4 v[82:85], v[18:19], off offset:1024
	global_load_dwordx4 v[86:89], v[18:19], off offset:1280
.Latt_st_c2:
	s_andn2_b64 exec, s[0:1], s[74:75]
	s_cbranch_execz .Latt_st_n2
	v_add_u32_e32 v18, vcc_lo, v147
	v_ashrrev_i32_e32 v19, 31, v18
	v_lshlrev_b64 v[22:23], 9, v[18:19]
	v_lshl_or_b32 v22, v8, 2, v22
	v_lshl_add_u64 v[18:19], s[56:57], 0, v[22:23]
	v_lshl_add_u64 v[20:21], s[78:79], 0, v[22:23]
	global_load_dwordx4 v[90:93], v[18:19], off
	global_load_dwordx4 v[94:97], v[18:19], off offset:16
	global_load_dwordx4 v[98:101], v[20:21], off
	global_load_dwordx4 v[102:105], v[20:21], off offset:16
.Latt_st_n2:
	s_waitcnt vmcnt(0)
	v_readlane_b32 s74, v253, 36
	v_readlane_b32 s75, v253, 37
	s_nop 0
	s_andn2_b64 exec, s[0:1], s[74:75]
	v_cvt_pk_bf16_f32 v0, v42, v43
	v_cvt_pk_bf16_f32 v1, v44, v45
	v_cvt_pk_bf16_f32 v2, v46, v47
	v_cvt_pk_bf16_f32 v3, v48, v49
	v_cvt_pk_bf16_f32 v4, v50, v51
	v_cvt_pk_bf16_f32 v5, v52, v53
	v_cvt_pk_bf16_f32 v6, v54, v55
	v_cvt_pk_bf16_f32 v7, v56, v57
	s_mov_b64 exec, s[0:1]
	v_add_u32_e32 v9, v154, v141
	v_add_u32_e32 v10, v154, v143
	ds_write_b128 v9, v[0:3] offset:33792
	ds_write_b128 v10, v[4:7] offset:61440
	v_readlane_b32 s74, v253, 40
	v_readlane_b32 s75, v253, 41
	s_nop 0
	s_andn2_b64 exec, s[0:1], s[74:75]
	v_cvt_pk_bf16_f32 v58, v66, v67
	v_cvt_pk_bf16_f32 v59, v68, v69
	v_cvt_pk_bf16_f32 v60, v70, v71
	v_cvt_pk_bf16_f32 v61, v72, v73
	v_cvt_pk_bf16_f32 v62, v74, v75
	v_cvt_pk_bf16_f32 v63, v76, v77
	v_cvt_pk_bf16_f32 v64, v78, v79
	v_cvt_pk_bf16_f32 v65, v80, v81
	s_mov_b64 exec, s[0:1]
	v_add_u32_e32 v9, v154, v145
	v_add_u32_e32 v10, v154, v146
	ds_write_b128 v9, v[58:61] offset:33792
	ds_write_b128 v10, v[62:65] offset:61440
	s_andn2_b64 exec, s[0:1], s[82:83]
	v_cvt_pk_bf16_f32 v82, v90, v91
	v_cvt_pk_bf16_f32 v83, v92, v93
	v_cvt_pk_bf16_f32 v84, v94, v95
	v_cvt_pk_bf16_f32 v85, v96, v97
	v_cvt_pk_bf16_f32 v86, v98, v99
	v_cvt_pk_bf16_f32 v87, v100, v101
	v_cvt_pk_bf16_f32 v88, v102, v103
	v_cvt_pk_bf16_f32 v89, v104, v105
	s_mov_b64 exec, s[0:1]
	v_add_u32_e32 v9, v154, v148
	v_add_u32_e32 v10, v154, v149
	ds_write_b128 v9, v[82:85] offset:33792
	ds_write_b128 v10, v[86:89] offset:61440
